# v053 + main GEMM K-loop head aligned to 64 bytes (unexecuted padding after the peeled iteration's branch)
# speedup vs baseline: 1.0060x; 1.0060x over previous
; #define PG8_STAGE(bufoff, gbase, voff) do { _Pragma("unroll") for (int _i = 0; _i < 2; ++_i) \
;         __builtin_amdgcn_global_load_lds((const unsigned*)((const char*)(gbase) + (voff)[_i]), (LAS unsigned*)(lds + (bufoff) + ldsw + _i * 8192), 16, 0, 0); } while (0)
; #define PG8_LDA(dst, b, h) do { _Pragma("unroll") for (int m = 0; m < 4; ++m) _Pragma("unroll") for (int k = 0; k < 2; ++k) dst[m][k] = *(const LAS bf16x8*)(lds + PG8_SA(b, h) + aoff + m * 2048 + k * 1024); } while (0)
; #define PG8_LDB(dst, b, h) do { _Pragma("unroll") for (int n = 0; n < 2; ++n) _Pragma("unroll") for (int k = 0; k < 2; ++k) dst[n][k] = *(const LAS bf16x8*)(lds + PG8_SB(b, h) + boff + n * 2048 + k * 1024); } while (0)
; #define PG8_MMA(ai, bj, At, Bt) do { __builtin_amdgcn_s_setprio(1); _Pragma("unroll") for (int m = 0; m < 4; ++m) _Pragma("unroll") for (int n = 0; n < 2; ++n) _Pragma("unroll") for (int k = 0; k < 2; ++k) \
;         acc[ai][bj][m][n] = __builtin_amdgcn_mfma_f32_16x16x32_bf16(Bt[n][k], At[m][k], acc[ai][bj][m][n], 0, 0, 0); __builtin_amdgcn_s_setprio(0); } while (0)
; #define PG8_WAIT_V(n) asm volatile("s_waitcnt vmcnt(" #n ")" ::: "memory")
; #define PG8_WAIT_L(n) asm volatile("s_waitcnt lgkmcnt(" #n ")" ::: "memory")
; #define PG8_BAR __builtin_amdgcn_s_barrier()
; __device__ __forceinline__ void gemm_phase(LAS unsigned char* lds, const Params& p, const Sched& S, float alpha, const int TIDX) {
;     ...
;         for (int t = 0; t < nt; t += 2) {
;             const bool last = (t == nt - 2);
;             const char* a1 = cA + (size_t)(t + 1) * kstep;
;             const char* a2 = last ? nA : cA + (size_t)(t + 2) * kstep; const char* b2 = last ? nB : cB + (size_t)(t + 2) * kstep;
;             const char* a3 = a2 + kstep; const char* b3 = b2 + kstep;
;             PG8_LDB(B0, 0, 0); PG8_SCHED; PG8_LDA(At, 0, 0); PG8_STAGE(PG8_SA(1, 1), a1 + hstep, voffA);
;             PG8_WAIT_L(8); PG8_BAR; PG8_WAIT_L(0); PG8_MMA(0, 0, At, B0); PG8_BAR; PG8_SCHED;
;             PG8_LDB(B1, 0, 1); PG8_STAGE(PG8_SB(0, 0), b2, voffB);
;             PG8_BAR; PG8_WAIT_L(0); PG8_MMA(0, 1, At, B1); PG8_BAR;
;             PG8_LDA(At, 0, 1); PG8_STAGE(PG8_SA(0, 0), a2, voffA);
;             PG8_BAR; PG8_WAIT_L(0); PG8_MMA(1, 0, At, B0); PG8_BAR; PG8_SCHED;
;             PG8_STAGE(PG8_SB(0, 1), b2 + hstep, voffB);
;             PG8_WAIT_V(6); PG8_BAR; PG8_MMA(1, 1, At, B1); PG8_BAR;
.Lgemm_prio_done:
	s_add_i32 s57, s48, 2
	s_add_u32 s50, s6, 0x80
	s_addc_u32 s49, s7, 0
	s_add_i32 s74, 0, 0x10000
	v_add_u32_e32 v0, s74, v200
	ds_read_b128 v[130:133], v0
	ds_read_b128 v[134:137], v0 offset:1024
	ds_read_b128 v[154:157], v0 offset:2048
	ds_read_b128 v[158:161], v0 offset:3072
	s_cmp_eq_u32 s38, s48
	s_cselect_b32 s48, s44, s50
	s_cselect_b32 s49, s45, s49
	s_cselect_b32 s51, s47, s56
	s_cselect_b32 s50, s46, s39
	v_lshl_add_u64 v[166:167], s[6:7], 0, v[150:151]
	s_add_i32 m0, s35, 0xc000
	ds_read_b128 v[162:165], v202
	ds_read_b128 v[170:173], v202 offset:1024
	ds_read_b128 v[174:177], v202 offset:2048
	ds_read_b128 v[178:181], v202 offset:3072
	ds_read_b128 v[182:185], v202 offset:4096
	ds_read_b128 v[204:207], v202 offset:5120
	ds_read_b128 v[208:211], v202 offset:6144
	ds_read_b128 v[212:215], v202 offset:7168
	global_load_lds_dwordx4 v[166:167], off
	v_lshl_add_u64 v[166:167], s[6:7], 0, v[152:153]
	s_add_i32 m0, s35, 0xe000
	s_nop 0
	global_load_lds_dwordx4 v[166:167], off
	s_waitcnt lgkmcnt(8)
	s_barrier
	s_waitcnt lgkmcnt(0)
	v_mfma_f32_16x16x32_bf16 v[126:129], v[130:133], v[162:165], 0
	v_mfma_f32_16x16x32_bf16 v[118:121], v[154:157], v[162:165], 0
	v_mfma_f32_16x16x32_bf16 v[110:113], v[130:133], v[174:177], 0
	v_mfma_f32_16x16x32_bf16 v[102:105], v[154:157], v[174:177], 0
	v_mfma_f32_16x16x32_bf16 v[94:97], v[130:133], v[182:185], 0
	v_mfma_f32_16x16x32_bf16 v[86:89], v[154:157], v[182:185], 0
	v_mfma_f32_16x16x32_bf16 v[78:81], v[130:133], v[208:211], 0
	v_mfma_f32_16x16x32_bf16 v[70:73], v[154:157], v[208:211], 0
	v_mfma_f32_16x16x32_bf16 v[126:129], v[134:137], v[170:173], v[126:129]
	v_mfma_f32_16x16x32_bf16 v[118:121], v[158:161], v[170:173], v[118:121]
	v_mfma_f32_16x16x32_bf16 v[110:113], v[134:137], v[178:181], v[110:113]
	v_mfma_f32_16x16x32_bf16 v[102:105], v[158:161], v[178:181], v[102:105]
	v_mfma_f32_16x16x32_bf16 v[94:97], v[134:137], v[204:207], v[94:97]
	v_mfma_f32_16x16x32_bf16 v[86:89], v[158:161], v[204:207], v[86:89]
	v_mfma_f32_16x16x32_bf16 v[78:81], v[134:137], v[212:215], v[78:81]
	v_mfma_f32_16x16x32_bf16 v[70:73], v[158:161], v[212:215], v[70:73]
	s_barrier
	s_add_i32 s75, 0, 0x14000
	s_add_i32 s74, s74, s34
	v_add_u32_e32 v0, s75, v200
	v_lshl_add_u64 v[166:167], s[50:51], 0, v[140:141]
	s_mov_b32 m0, s74
	ds_read_b128 v[216:219], v0
	ds_read_b128 v[220:223], v0 offset:1024
	ds_read_b128 v[224:227], v0 offset:2048
	ds_read_b128 v[228:231], v0 offset:3072
	global_load_lds_dwordx4 v[166:167], off
	v_lshl_add_u64 v[186:187], s[50:51], 0, v[144:145]
	s_add_i32 m0, s74, 0x2000
	s_nop 0
	global_load_lds_dwordx4 v[186:187], off
	s_barrier
	s_waitcnt lgkmcnt(0)
	v_mfma_f32_16x16x32_bf16 v[122:125], v[216:219], v[162:165], 0
	v_mfma_f32_16x16x32_bf16 v[114:117], v[224:227], v[162:165], 0
	v_mfma_f32_16x16x32_bf16 v[106:109], v[216:219], v[174:177], 0
	v_mfma_f32_16x16x32_bf16 v[98:101], v[224:227], v[174:177], 0
	v_mfma_f32_16x16x32_bf16 v[90:93], v[216:219], v[182:185], 0
	v_mfma_f32_16x16x32_bf16 v[82:85], v[224:227], v[182:185], 0
	v_mfma_f32_16x16x32_bf16 v[74:77], v[216:219], v[208:211], 0
	v_mfma_f32_16x16x32_bf16 v[66:69], v[224:227], v[208:211], 0
	v_mfma_f32_16x16x32_bf16 v[122:125], v[220:223], v[170:173], v[122:125]
	v_mfma_f32_16x16x32_bf16 v[114:117], v[228:231], v[170:173], v[114:117]
	v_mfma_f32_16x16x32_bf16 v[106:109], v[220:223], v[178:181], v[106:109]
	v_mfma_f32_16x16x32_bf16 v[98:101], v[228:231], v[178:181], v[98:101]
	v_mfma_f32_16x16x32_bf16 v[90:93], v[220:223], v[204:207], v[90:93]
	v_mfma_f32_16x16x32_bf16 v[82:85], v[228:231], v[204:207], v[82:85]
	v_mfma_f32_16x16x32_bf16 v[74:77], v[220:223], v[212:215], v[74:77]
	v_mfma_f32_16x16x32_bf16 v[66:69], v[228:231], v[212:215], v[66:69]
	s_mov_b32 m0, s35
	v_lshl_add_u64 v[232:233], s[48:49], 0, v[138:139]
	s_barrier
	ds_read_b128 v[162:165], v202 offset:16384
	ds_read_b128 v[170:173], v202 offset:17408
	ds_read_b128 v[174:177], v202 offset:18432
	ds_read_b128 v[178:181], v202 offset:19456
	ds_read_b128 v[182:185], v202 offset:20480
	ds_read_b128 v[204:207], v202 offset:21504
	ds_read_b128 v[208:211], v202 offset:22528
	ds_read_b128 v[212:215], v202 offset:23552
	global_load_lds_dwordx4 v[232:233], off
	v_lshl_add_u64 v[234:235], s[48:49], 0, v[142:143]
	s_mov_b32 m0, s36
	s_nop 0
	global_load_lds_dwordx4 v[234:235], off
	s_barrier
	s_waitcnt lgkmcnt(0)
	v_mfma_f32_16x16x32_bf16 v[62:65], v[130:133], v[162:165], 0
	v_mfma_f32_16x16x32_bf16 v[54:57], v[154:157], v[162:165], 0
	v_mfma_f32_16x16x32_bf16 v[46:49], v[130:133], v[174:177], 0
	v_mfma_f32_16x16x32_bf16 v[38:41], v[154:157], v[174:177], 0
	v_mfma_f32_16x16x32_bf16 v[30:33], v[130:133], v[182:185], 0
	v_mfma_f32_16x16x32_bf16 v[22:25], v[154:157], v[182:185], 0
	v_mfma_f32_16x16x32_bf16 v[14:17], v[130:133], v[208:211], 0
	v_mfma_f32_16x16x32_bf16 v[6:9], v[154:157], v[208:211], 0
	v_mfma_f32_16x16x32_bf16 v[62:65], v[134:137], v[170:173], v[62:65]
	v_mfma_f32_16x16x32_bf16 v[54:57], v[158:161], v[170:173], v[54:57]
	v_mfma_f32_16x16x32_bf16 v[46:49], v[134:137], v[178:181], v[46:49]
	v_mfma_f32_16x16x32_bf16 v[38:41], v[158:161], v[178:181], v[38:41]
	v_mfma_f32_16x16x32_bf16 v[30:33], v[134:137], v[204:207], v[30:33]
	v_mfma_f32_16x16x32_bf16 v[22:25], v[158:161], v[204:207], v[22:25]
	v_mfma_f32_16x16x32_bf16 v[14:17], v[134:137], v[212:215], v[14:17]
	v_mfma_f32_16x16x32_bf16 v[6:9], v[158:161], v[212:215], v[6:9]
	s_barrier
	s_add_u32 s50, s50, s20
	s_addc_u32 s51, s51, 0
	s_add_i32 s74, s75, s34
	v_lshl_add_u64 v[236:237], s[50:51], 0, v[140:141]
	s_mov_b32 m0, s74
	v_lshl_add_u64 v[238:239], s[50:51], 0, v[144:145]
	global_load_lds_dwordx4 v[236:237], off
	s_add_i32 m0, s74, 0x2000
	s_nop 0
	global_load_lds_dwordx4 v[238:239], off
	s_waitcnt vmcnt(6)
	s_barrier
; #define PG8_STAGE(bufoff, gbase, voff) do { _Pragma("unroll") for (int _i = 0; _i < 2; ++_i) \
;         __builtin_amdgcn_global_load_lds((const unsigned*)((const char*)(gbase) + (voff)[_i]), (LAS unsigned*)(lds + (bufoff) + ldsw + _i * 8192), 16, 0, 0); } while (0)
; #define PG8_LDA(dst, b, h) do { _Pragma("unroll") for (int m = 0; m < 4; ++m) _Pragma("unroll") for (int k = 0; k < 2; ++k) dst[m][k] = *(const LAS bf16x8*)(lds + PG8_SA(b, h) + aoff + m * 2048 + k * 1024); } while (0)
; #define PG8_LDB(dst, b, h) do { _Pragma("unroll") for (int n = 0; n < 2; ++n) _Pragma("unroll") for (int k = 0; k < 2; ++k) dst[n][k] = *(const LAS bf16x8*)(lds + PG8_SB(b, h) + boff + n * 2048 + k * 1024); } while (0)
; #define PG8_MMA(ai, bj, At, Bt) do { __builtin_amdgcn_s_setprio(1); _Pragma("unroll") for (int m = 0; m < 4; ++m) _Pragma("unroll") for (int n = 0; n < 2; ++n) _Pragma("unroll") for (int k = 0; k < 2; ++k) \
;         acc[ai][bj][m][n] = __builtin_amdgcn_mfma_f32_16x16x32_bf16(Bt[n][k], At[m][k], acc[ai][bj][m][n], 0, 0, 0); __builtin_amdgcn_s_setprio(0); } while (0)
; #define PG8_WAIT_V(n) asm volatile("s_waitcnt vmcnt(" #n ")" ::: "memory")
; #define PG8_WAIT_L(n) asm volatile("s_waitcnt lgkmcnt(" #n ")" ::: "memory")
; #define PG8_BAR __builtin_amdgcn_s_barrier()
; #define PG8_SCHED __builtin_amdgcn_sched_barrier(0)
; __device__ __forceinline__ void gemm_phase(LAS unsigned char* lds, const Params& p, const Sched& S, float alpha, const int TIDX) {
;     ...
;             PG8_WAIT_V(6); PG8_BAR; PG8_MMA(1, 1, At, B1); PG8_BAR;
;             PG8_LDB(B0, 1, 0); PG8_SCHED; PG8_LDA(At, 1, 0); PG8_STAGE(PG8_SA(0, 1), a2 + hstep, voffA);
;             PG8_WAIT_L(8); PG8_BAR; PG8_WAIT_L(0); PG8_MMA(0, 0, At, B0); PG8_BAR; PG8_SCHED;
	v_mfma_f32_16x16x32_bf16 v[58:61], v[216:219], v[162:165], 0
	v_mfma_f32_16x16x32_bf16 v[50:53], v[224:227], v[162:165], 0
	v_mfma_f32_16x16x32_bf16 v[42:45], v[216:219], v[174:177], 0
	v_mfma_f32_16x16x32_bf16 v[34:37], v[224:227], v[174:177], 0
	v_mfma_f32_16x16x32_bf16 v[26:29], v[216:219], v[182:185], 0
	v_mfma_f32_16x16x32_bf16 v[18:21], v[224:227], v[182:185], 0
	v_mfma_f32_16x16x32_bf16 v[10:13], v[216:219], v[208:211], 0
	v_mfma_f32_16x16x32_bf16 v[2:5], v[224:227], v[208:211], 0
	v_mfma_f32_16x16x32_bf16 v[58:61], v[220:223], v[170:173], v[58:61]
	v_mfma_f32_16x16x32_bf16 v[50:53], v[228:231], v[170:173], v[50:53]
	v_mfma_f32_16x16x32_bf16 v[42:45], v[220:223], v[178:181], v[42:45]
	v_mfma_f32_16x16x32_bf16 v[34:37], v[228:231], v[178:181], v[34:37]
	v_mfma_f32_16x16x32_bf16 v[26:29], v[220:223], v[204:207], v[26:29]
	v_mfma_f32_16x16x32_bf16 v[18:21], v[228:231], v[204:207], v[18:21]
	v_mfma_f32_16x16x32_bf16 v[10:13], v[220:223], v[212:215], v[10:13]
	v_mfma_f32_16x16x32_bf16 v[2:5], v[228:231], v[212:215], v[2:5]
	s_add_i32 s50, 0, 0x18000
	v_add_u32_e32 v0, s50, v200
	s_barrier
	ds_read_b128 v[130:133], v0
	ds_read_b128 v[134:137], v0 offset:1024
	ds_read_b128 v[154:157], v0 offset:2048
	ds_read_b128 v[158:161], v0 offset:3072
	s_add_u32 s48, s48, s20
	s_addc_u32 s49, s49, 0
	s_mov_b32 m0, s37
	v_lshl_add_u64 v[216:217], s[48:49], 0, v[138:139]
	ds_read_b128 v[162:165], v202 offset:32768
	ds_read_b128 v[170:173], v202 offset:33792
	ds_read_b128 v[174:177], v202 offset:34816
	ds_read_b128 v[178:181], v202 offset:35840
	ds_read_b128 v[182:185], v202 offset:36864
	ds_read_b128 v[204:207], v202 offset:37888
	ds_read_b128 v[208:211], v202 offset:38912
	ds_read_b128 v[212:215], v202 offset:39936
	global_load_lds_dwordx4 v[216:217], off
	v_lshl_add_u64 v[216:217], s[48:49], 0, v[142:143]
	s_mov_b32 m0, s24
	s_nop 0
	global_load_lds_dwordx4 v[216:217], off
	s_waitcnt lgkmcnt(8)
	s_barrier
	s_waitcnt lgkmcnt(0)
	v_mfma_f32_16x16x32_bf16 v[126:129], v[130:133], v[162:165], v[126:129]
	v_mfma_f32_16x16x32_bf16 v[118:121], v[154:157], v[162:165], v[118:121]
	v_mfma_f32_16x16x32_bf16 v[110:113], v[130:133], v[174:177], v[110:113]
	v_mfma_f32_16x16x32_bf16 v[102:105], v[154:157], v[174:177], v[102:105]
	v_mfma_f32_16x16x32_bf16 v[94:97], v[130:133], v[182:185], v[94:97]
	v_mfma_f32_16x16x32_bf16 v[86:89], v[154:157], v[182:185], v[86:89]
	v_mfma_f32_16x16x32_bf16 v[78:81], v[130:133], v[208:211], v[78:81]
	v_mfma_f32_16x16x32_bf16 v[70:73], v[154:157], v[208:211], v[70:73]
	v_mfma_f32_16x16x32_bf16 v[126:129], v[134:137], v[170:173], v[126:129]
	v_mfma_f32_16x16x32_bf16 v[118:121], v[158:161], v[170:173], v[118:121]
	v_mfma_f32_16x16x32_bf16 v[110:113], v[134:137], v[178:181], v[110:113]
	v_mfma_f32_16x16x32_bf16 v[102:105], v[158:161], v[178:181], v[102:105]
	v_mfma_f32_16x16x32_bf16 v[94:97], v[134:137], v[204:207], v[94:97]
	v_mfma_f32_16x16x32_bf16 v[86:89], v[158:161], v[204:207], v[86:89]
	v_mfma_f32_16x16x32_bf16 v[78:81], v[134:137], v[212:215], v[78:81]
	v_mfma_f32_16x16x32_bf16 v[70:73], v[158:161], v[212:215], v[70:73]
	s_barrier
	s_add_i32 s48, 0, 0x1c000
	s_add_i32 s49, s50, s34
	v_add_u32_e32 v0, s48, v200
	v_lshl_add_u64 v[166:167], v[166:167], 0, s[88:89]
	s_mov_b32 m0, s49
	ds_read_b128 v[216:219], v0
	ds_read_b128 v[220:223], v0 offset:1024
	ds_read_b128 v[224:227], v0 offset:2048
	ds_read_b128 v[228:231], v0 offset:3072
	global_load_lds_dwordx4 v[166:167], off
	v_lshl_add_u64 v[166:167], v[186:187], 0, s[88:89]
	s_add_i32 m0, s49, 0x2000
	s_nop 0
	global_load_lds_dwordx4 v[166:167], off
	s_barrier
; #define PG8_STAGE(bufoff, gbase, voff) do { _Pragma("unroll") for (int _i = 0; _i < 2; ++_i) \
;         __builtin_amdgcn_global_load_lds((const unsigned*)((const char*)(gbase) + (voff)[_i]), (LAS unsigned*)(lds + (bufoff) + ldsw + _i * 8192), 16, 0, 0); } while (0)
; #define PG8_LDA(dst, b, h) do { _Pragma("unroll") for (int m = 0; m < 4; ++m) _Pragma("unroll") for (int k = 0; k < 2; ++k) dst[m][k] = *(const LAS bf16x8*)(lds + PG8_SA(b, h) + aoff + m * 2048 + k * 1024); } while (0)
; #define PG8_LDB(dst, b, h) do { _Pragma("unroll") for (int n = 0; n < 2; ++n) _Pragma("unroll") for (int k = 0; k < 2; ++k) dst[n][k] = *(const LAS bf16x8*)(lds + PG8_SB(b, h) + boff + n * 2048 + k * 1024); } while (0)
; #define PG8_MMA(ai, bj, At, Bt) do { __builtin_amdgcn_s_setprio(1); _Pragma("unroll") for (int m = 0; m < 4; ++m) _Pragma("unroll") for (int n = 0; n < 2; ++n) _Pragma("unroll") for (int k = 0; k < 2; ++k) \
;         acc[ai][bj][m][n] = __builtin_amdgcn_mfma_f32_16x16x32_bf16(Bt[n][k], At[m][k], acc[ai][bj][m][n], 0, 0, 0); __builtin_amdgcn_s_setprio(0); } while (0)
; #define PG8_WAIT_V(n) asm volatile("s_waitcnt vmcnt(" #n ")" ::: "memory")
; #define PG8_WAIT_L(n) asm volatile("s_waitcnt lgkmcnt(" #n ")" ::: "memory")
; #define PG8_BAR __builtin_amdgcn_s_barrier()
; #define PG8_SCHED __builtin_amdgcn_sched_barrier(0)
; __device__ __forceinline__ void gemm_phase(LAS unsigned char* lds, const Params& p, const Sched& S, float alpha, const int TIDX) {
;     ...
;             PG8_WAIT_L(8); PG8_BAR; PG8_WAIT_L(0); PG8_MMA(0, 0, At, B0); PG8_BAR; PG8_SCHED;
;             PG8_LDB(B1, 1, 1); PG8_STAGE(PG8_SB(1, 0), b3, voffB);
;             PG8_BAR; PG8_WAIT_L(0); PG8_MMA(0, 1, At, B1); PG8_BAR;
;             PG8_LDA(At, 1, 1); PG8_STAGE(PG8_SA(1, 0), a3, voffA);
;             PG8_BAR; PG8_WAIT_L(0); PG8_MMA(1, 0, At, B0); PG8_BAR; PG8_SCHED;
;             PG8_STAGE(PG8_SB(1, 1), b3 + hstep, voffB);
;             PG8_WAIT_V(6); PG8_BAR; PG8_MMA(1, 1, At, B1); PG8_BAR;
;         }
	s_waitcnt lgkmcnt(0)
	v_mfma_f32_16x16x32_bf16 v[122:125], v[216:219], v[162:165], v[122:125]
	v_mfma_f32_16x16x32_bf16 v[114:117], v[224:227], v[162:165], v[114:117]
	v_mfma_f32_16x16x32_bf16 v[106:109], v[216:219], v[174:177], v[106:109]
	v_mfma_f32_16x16x32_bf16 v[98:101], v[224:227], v[174:177], v[98:101]
	v_mfma_f32_16x16x32_bf16 v[90:93], v[216:219], v[182:185], v[90:93]
	v_mfma_f32_16x16x32_bf16 v[82:85], v[224:227], v[182:185], v[82:85]
	v_mfma_f32_16x16x32_bf16 v[74:77], v[216:219], v[208:211], v[74:77]
	v_mfma_f32_16x16x32_bf16 v[66:69], v[224:227], v[208:211], v[66:69]
	v_mfma_f32_16x16x32_bf16 v[122:125], v[220:223], v[170:173], v[122:125]
	v_mfma_f32_16x16x32_bf16 v[114:117], v[228:231], v[170:173], v[114:117]
	v_mfma_f32_16x16x32_bf16 v[106:109], v[220:223], v[178:181], v[106:109]
	v_mfma_f32_16x16x32_bf16 v[98:101], v[228:231], v[178:181], v[98:101]
	v_mfma_f32_16x16x32_bf16 v[90:93], v[220:223], v[204:207], v[90:93]
	v_mfma_f32_16x16x32_bf16 v[82:85], v[228:231], v[204:207], v[82:85]
	v_mfma_f32_16x16x32_bf16 v[74:77], v[220:223], v[212:215], v[74:77]
	v_mfma_f32_16x16x32_bf16 v[66:69], v[228:231], v[212:215], v[66:69]
	s_mov_b32 m0, s25
	v_lshl_add_u64 v[166:167], v[232:233], 0, s[88:89]
	s_barrier
	ds_read_b128 v[162:165], v202 offset:49152
	ds_read_b128 v[170:173], v202 offset:50176
	ds_read_b128 v[174:177], v202 offset:51200
	ds_read_b128 v[178:181], v202 offset:52224
	ds_read_b128 v[182:185], v202 offset:53248
	ds_read_b128 v[204:207], v202 offset:54272
	ds_read_b128 v[208:211], v202 offset:55296
	ds_read_b128 v[212:215], v202 offset:56320
	global_load_lds_dwordx4 v[166:167], off
	v_lshl_add_u64 v[166:167], v[234:235], 0, s[88:89]
	s_mov_b32 m0, s68
	s_nop 0
	global_load_lds_dwordx4 v[166:167], off
	s_barrier
	s_waitcnt lgkmcnt(0)
	v_mfma_f32_16x16x32_bf16 v[62:65], v[130:133], v[162:165], v[62:65]
	v_mfma_f32_16x16x32_bf16 v[54:57], v[154:157], v[162:165], v[54:57]
	v_mfma_f32_16x16x32_bf16 v[46:49], v[130:133], v[174:177], v[46:49]
	v_mfma_f32_16x16x32_bf16 v[38:41], v[154:157], v[174:177], v[38:41]
	v_mfma_f32_16x16x32_bf16 v[30:33], v[130:133], v[182:185], v[30:33]
	v_mfma_f32_16x16x32_bf16 v[22:25], v[154:157], v[182:185], v[22:25]
	v_mfma_f32_16x16x32_bf16 v[14:17], v[130:133], v[208:211], v[14:17]
	v_mfma_f32_16x16x32_bf16 v[6:9], v[154:157], v[208:211], v[6:9]
	v_mfma_f32_16x16x32_bf16 v[62:65], v[134:137], v[170:173], v[62:65]
	v_mfma_f32_16x16x32_bf16 v[54:57], v[158:161], v[170:173], v[54:57]
	v_mfma_f32_16x16x32_bf16 v[46:49], v[134:137], v[178:181], v[46:49]
	v_mfma_f32_16x16x32_bf16 v[38:41], v[158:161], v[178:181], v[38:41]
	v_mfma_f32_16x16x32_bf16 v[30:33], v[134:137], v[204:207], v[30:33]
	v_mfma_f32_16x16x32_bf16 v[22:25], v[158:161], v[204:207], v[22:25]
	v_mfma_f32_16x16x32_bf16 v[14:17], v[134:137], v[212:215], v[14:17]
	v_mfma_f32_16x16x32_bf16 v[6:9], v[158:161], v[212:215], v[6:9]
	s_barrier
	s_add_i32 s48, s48, s34
	v_lshl_add_u64 v[130:131], v[236:237], 0, s[88:89]
	s_mov_b32 m0, s48
	s_nop 0
	global_load_lds_dwordx4 v[130:131], off
	v_lshl_add_u64 v[130:131], v[238:239], 0, s[88:89]
	s_add_i32 m0, s48, 0x2000
	s_nop 0
	global_load_lds_dwordx4 v[130:131], off
	s_waitcnt vmcnt(6)
	s_barrier
	v_mfma_f32_16x16x32_bf16 v[58:61], v[216:219], v[162:165], v[58:61]
	v_mfma_f32_16x16x32_bf16 v[50:53], v[224:227], v[162:165], v[50:53]
	v_mfma_f32_16x16x32_bf16 v[42:45], v[216:219], v[174:177], v[42:45]
	v_mfma_f32_16x16x32_bf16 v[34:37], v[224:227], v[174:177], v[34:37]
	v_mfma_f32_16x16x32_bf16 v[26:29], v[216:219], v[182:185], v[26:29]
	v_mfma_f32_16x16x32_bf16 v[18:21], v[224:227], v[182:185], v[18:21]
	v_mfma_f32_16x16x32_bf16 v[10:13], v[216:219], v[208:211], v[10:13]
	v_mfma_f32_16x16x32_bf16 v[2:5], v[224:227], v[208:211], v[2:5]
	v_mfma_f32_16x16x32_bf16 v[58:61], v[220:223], v[170:173], v[58:61]
	v_mfma_f32_16x16x32_bf16 v[50:53], v[228:231], v[170:173], v[50:53]
	v_mfma_f32_16x16x32_bf16 v[42:45], v[220:223], v[178:181], v[42:45]
	v_mfma_f32_16x16x32_bf16 v[34:37], v[228:231], v[178:181], v[34:37]
	v_mfma_f32_16x16x32_bf16 v[26:29], v[220:223], v[204:207], v[26:29]
	v_mfma_f32_16x16x32_bf16 v[18:21], v[228:231], v[204:207], v[18:21]
	v_mfma_f32_16x16x32_bf16 v[10:13], v[220:223], v[212:215], v[10:13]
	v_mfma_f32_16x16x32_bf16 v[2:5], v[228:231], v[212:215], v[2:5]
	s_add_u32 s6, s6, 0x100
	s_addc_u32 s7, s7, 0
	s_add_u32 s39, s39, 0x100
	s_addc_u32 s56, s56, 0
	s_cmp_ge_i32 s57, s79
	s_mov_b32 s48, s57
	s_barrier
	s_cbranch_scc0 .LBB0_289
	s_branch .LBB0_291
	.p2align	6
